# swiglu epilogue L2 warm-up widened to next tile weight K-tiles 2..9
# speedup vs baseline: 1.0174x; 1.0016x over previous
; __device__ __forceinline__ unsigned cvt_pk_bf16(float lo, float hi) { unsigned r; asm volatile("v_cvt_pk_bf16_f32 %0, %1, %2" : "=v"(r) : "v"(lo), "v"(hi)); return r; }
;     __device__ __forceinline__ void operator()(const f32x4 (&acc)[2][2][4][2], const Unit& u, int wr, int wc, int fr, int fq) const {
;     ...
;             for (int m = 0; m < 4; ++m) { const int row = row0 + ai * HALF + m * 16; const float rs = row_rstd(ssq, row, fr, fq), rs2 = rs * rs, nrl = -1.4426950408889634f * rs;
;                 float o[8];
; #pragma unroll
;                 for (int n = 0; n < 2; ++n) { const f32x4 g = acc[ai][0][m][n], gu = g * acc[ai][1][m][n] * rs2;
; #pragma unroll
;                     for (int j = 0; j < 4; ++j) o[4 * n + j] = gu[j] * __builtin_amdgcn_rcpf(1.0f + __builtin_amdgcn_exp2f(g[j] * nrl)); }
;                 u32x4 w; w.x = cvt_pk_bf16(o[0], o[1]); w.y = cvt_pk_bf16(o[2], o[3]); w.z = cvt_pk_bf16(o[4], o[5]); w.w = cvt_pk_bf16(o[6], o[7]);
;                 *(u32x4*)(ACT + (size_t)row * 5632 + ch0) = w;
.Lsw1_have:
	s_lshl_b32 s4, s78, 2
	s_lshl_b32 s5, s82, 1
	s_add_i32 s4, s4, s5
	v_add_u32_e32 v144, s4, v167
	v_lshrrev_b32_e32 v145, 4, v144
	v_and_b32_e32 v144, 15, v144
	v_lshlrev_b32_e32 v144, 6, v144
	v_lshl_add_u32 v144, v145, 12, v144
	s_and_b32 s4, s26, 7
	s_lshl_b32 s4, s4, 17
	v_add_u32_e32 v144, s4, v144
	s_mov_b32 s4, s57
	s_mov_b32 s5, s17
	s_nop 4
	global_load_dwordx4 v[242:245], v144, s[4:5] offset:256
	global_load_dwordx4 v[246:249], v144, s[4:5] offset:272
	global_load_dwordx4 v[242:245], v144, s[4:5] offset:288
	global_load_dwordx4 v[246:249], v144, s[4:5] offset:304
	v_and_b32_e32 v153, 15, v167
	v_lshrrev_b32_e32 v154, 4, v167
	s_lshl_b32 s4, s26, 8
	s_add_i32 s4, s4, s78
	v_or_b32_e32 v155, s4, v153
	s_lshl_b32 s4, s55, 7
	s_or_b32 s4, s4, s82
	v_lshl_add_u32 v162, v154, 3, s4
	v_lshlrev_b32_e32 v162, 1, v162
	v_mul_u32_u24_e32 v163, 0x2c00, v155
	v_add_u32_e32 v162, v162, v163
	v_mov_b32_e32 v164, v162
	v_mul_f32_e32 v124, v116, v124
	v_mul_f32_e32 v125, v117, v125
	v_mul_f32_e32 v126, v118, v126
	v_mul_f32_e32 v127, v119, v127
	v_mul_f32_e32 v120, v112, v120
	v_mul_f32_e32 v121, v113, v121
	v_mul_f32_e32 v122, v114, v122
	v_mul_f32_e32 v123, v115, v123
	v_mul_f32_e32 v116, v116, v226
	v_mul_f32_e32 v117, v117, v226
	v_mul_f32_e32 v118, v118, v226
	v_mul_f32_e32 v119, v119, v226
	v_mul_f32_e32 v112, v112, v226
	v_mul_f32_e32 v113, v113, v226
	v_mul_f32_e32 v114, v114, v226
	v_mul_f32_e32 v115, v115, v226
	v_exp_f32_e32 v116, v116
	v_exp_f32_e32 v117, v117
	v_exp_f32_e32 v118, v118
	v_exp_f32_e32 v119, v119
	v_exp_f32_e32 v112, v112
	v_exp_f32_e32 v113, v113
	v_exp_f32_e32 v114, v114
	v_exp_f32_e32 v115, v115
	v_add_f32_e32 v116, 1.0, v116
	v_add_f32_e32 v117, 1.0, v117
	v_add_f32_e32 v118, 1.0, v118
	v_add_f32_e32 v119, 1.0, v119
	v_add_f32_e32 v112, 1.0, v112
	v_add_f32_e32 v113, 1.0, v113
	v_add_f32_e32 v114, 1.0, v114
	v_add_f32_e32 v115, 1.0, v115
	v_rcp_f32_e32 v116, v116
	v_rcp_f32_e32 v117, v117
	v_rcp_f32_e32 v118, v118
	v_rcp_f32_e32 v119, v119
	v_rcp_f32_e32 v112, v112
	v_rcp_f32_e32 v113, v113
	v_rcp_f32_e32 v114, v114
	v_rcp_f32_e32 v115, v115
	v_mul_f32_e32 v124, v124, v234
	v_mul_f32_e32 v125, v125, v234
	v_mul_f32_e32 v126, v126, v234
	v_mul_f32_e32 v127, v127, v234
	v_mul_f32_e32 v120, v120, v234
	v_mul_f32_e32 v121, v121, v234
	v_mul_f32_e32 v122, v122, v234
	v_mul_f32_e32 v123, v123, v234
	v_mul_f32_e32 v124, v124, v116
	v_mul_f32_e32 v125, v125, v117
	v_mul_f32_e32 v126, v126, v118
	v_mul_f32_e32 v127, v127, v119
	v_mul_f32_e32 v120, v120, v112
	v_mul_f32_e32 v121, v121, v113
	v_mul_f32_e32 v122, v122, v114
	v_mul_f32_e32 v123, v123, v115
	v_cvt_pk_bf16_f32 v116, v124, v125
	v_cvt_pk_bf16_f32 v117, v126, v127
	v_cvt_pk_bf16_f32 v118, v120, v121
	v_cvt_pk_bf16_f32 v119, v122, v123
	global_store_dwordx4 v164, v[116:119], s[10:11]
	v_add_u32_e32 v165, 0x2c000, v162
	v_mul_f32_e32 v108, v100, v108
	v_mul_f32_e32 v109, v101, v109
	v_mul_f32_e32 v110, v102, v110
	v_mul_f32_e32 v111, v103, v111
	v_mul_f32_e32 v104, v96, v104
	v_mul_f32_e32 v105, v97, v105
	v_mul_f32_e32 v106, v98, v106
	v_mul_f32_e32 v107, v99, v107
	v_mul_f32_e32 v100, v100, v227
	v_mul_f32_e32 v101, v101, v227
	v_mul_f32_e32 v102, v102, v227
	v_mul_f32_e32 v103, v103, v227
	v_mul_f32_e32 v96, v96, v227
	v_mul_f32_e32 v97, v97, v227
	v_mul_f32_e32 v98, v98, v227
	v_mul_f32_e32 v99, v99, v227
	v_exp_f32_e32 v100, v100
	v_exp_f32_e32 v101, v101
	v_exp_f32_e32 v102, v102
	v_exp_f32_e32 v103, v103
	v_exp_f32_e32 v96, v96
	v_exp_f32_e32 v97, v97
	v_exp_f32_e32 v98, v98
	v_exp_f32_e32 v99, v99
	v_add_f32_e32 v100, 1.0, v100
	v_add_f32_e32 v101, 1.0, v101
	v_add_f32_e32 v102, 1.0, v102
	v_add_f32_e32 v103, 1.0, v103
	v_add_f32_e32 v96, 1.0, v96
	v_add_f32_e32 v97, 1.0, v97
	v_add_f32_e32 v98, 1.0, v98
	v_add_f32_e32 v99, 1.0, v99
	v_rcp_f32_e32 v100, v100
	v_rcp_f32_e32 v101, v101
	v_rcp_f32_e32 v102, v102
	v_rcp_f32_e32 v103, v103
	v_rcp_f32_e32 v96, v96
	v_rcp_f32_e32 v97, v97
	v_rcp_f32_e32 v98, v98
	v_rcp_f32_e32 v99, v99
	v_mul_f32_e32 v108, v108, v235
	v_mul_f32_e32 v109, v109, v235
	v_mul_f32_e32 v110, v110, v235
	v_mul_f32_e32 v111, v111, v235
	v_mul_f32_e32 v104, v104, v235
	v_mul_f32_e32 v105, v105, v235
	v_mul_f32_e32 v106, v106, v235
	v_mul_f32_e32 v107, v107, v235
	v_mul_f32_e32 v108, v108, v100
	v_mul_f32_e32 v109, v109, v101
	v_mul_f32_e32 v110, v110, v102
	v_mul_f32_e32 v111, v111, v103
	v_mul_f32_e32 v104, v104, v96
	v_mul_f32_e32 v105, v105, v97
	v_mul_f32_e32 v106, v106, v98
	v_mul_f32_e32 v107, v107, v99
	v_cvt_pk_bf16_f32 v100, v108, v109
	v_cvt_pk_bf16_f32 v101, v110, v111
	v_cvt_pk_bf16_f32 v102, v104, v105
	v_cvt_pk_bf16_f32 v103, v106, v107
	global_store_dwordx4 v165, v[100:103], s[10:11]
	v_add_u32_e32 v164, 0x58000, v162
	v_mul_f32_e32 v92, v84, v92
	v_mul_f32_e32 v93, v85, v93
	v_mul_f32_e32 v94, v86, v94
	v_mul_f32_e32 v95, v87, v95
	v_mul_f32_e32 v88, v80, v88
	v_mul_f32_e32 v89, v81, v89
	v_mul_f32_e32 v90, v82, v90
	v_mul_f32_e32 v91, v83, v91
	v_mul_f32_e32 v84, v84, v228
	v_mul_f32_e32 v85, v85, v228
	v_mul_f32_e32 v86, v86, v228
	v_mul_f32_e32 v87, v87, v228
	v_mul_f32_e32 v80, v80, v228
	v_mul_f32_e32 v81, v81, v228
	v_mul_f32_e32 v82, v82, v228
	v_mul_f32_e32 v83, v83, v228
	v_exp_f32_e32 v84, v84
	v_exp_f32_e32 v85, v85
	v_exp_f32_e32 v86, v86
	v_exp_f32_e32 v87, v87
	v_exp_f32_e32 v80, v80
	v_exp_f32_e32 v81, v81
	v_exp_f32_e32 v82, v82
	v_exp_f32_e32 v83, v83
	v_add_f32_e32 v84, 1.0, v84
	v_add_f32_e32 v85, 1.0, v85
	v_add_f32_e32 v86, 1.0, v86
	v_add_f32_e32 v87, 1.0, v87
	v_add_f32_e32 v80, 1.0, v80
	v_add_f32_e32 v81, 1.0, v81
	v_add_f32_e32 v82, 1.0, v82
	v_add_f32_e32 v83, 1.0, v83
	v_rcp_f32_e32 v84, v84
; __device__ __forceinline__ unsigned cvt_pk_bf16(float lo, float hi) { unsigned r; asm volatile("v_cvt_pk_bf16_f32 %0, %1, %2" : "=v"(r) : "v"(lo), "v"(hi)); return r; }
;     __device__ __forceinline__ void operator()(const f32x4 (&acc)[2][2][4][2], const Unit& u, int wr, int wc, int fr, int fq) const {
;     ...
;             for (int m = 0; m < 4; ++m) { const int row = row0 + ai * HALF + m * 16; const float rs = row_rstd(ssq, row, fr, fq), rs2 = rs * rs, nrl = -1.4426950408889634f * rs;
;                 float o[8];
; #pragma unroll
;                 for (int n = 0; n < 2; ++n) { const f32x4 g = acc[ai][0][m][n], gu = g * acc[ai][1][m][n] * rs2;
; #pragma unroll
;                     for (int j = 0; j < 4; ++j) o[4 * n + j] = gu[j] * __builtin_amdgcn_rcpf(1.0f + __builtin_amdgcn_exp2f(g[j] * nrl)); }
;                 u32x4 w; w.x = cvt_pk_bf16(o[0], o[1]); w.y = cvt_pk_bf16(o[2], o[3]); w.z = cvt_pk_bf16(o[4], o[5]); w.w = cvt_pk_bf16(o[6], o[7]);
;                 *(u32x4*)(ACT + (size_t)row * 5632 + ch0) = w;
	v_rcp_f32_e32 v85, v85
	v_rcp_f32_e32 v86, v86
	v_rcp_f32_e32 v87, v87
	v_rcp_f32_e32 v80, v80
	v_rcp_f32_e32 v81, v81
	v_rcp_f32_e32 v82, v82
	v_rcp_f32_e32 v83, v83
	v_mul_f32_e32 v92, v92, v236
	v_mul_f32_e32 v93, v93, v236
	v_mul_f32_e32 v94, v94, v236
	v_mul_f32_e32 v95, v95, v236
	v_mul_f32_e32 v88, v88, v236
	v_mul_f32_e32 v89, v89, v236
	v_mul_f32_e32 v90, v90, v236
	v_mul_f32_e32 v91, v91, v236
	v_mul_f32_e32 v92, v92, v84
	v_mul_f32_e32 v93, v93, v85
	v_mul_f32_e32 v94, v94, v86
	v_mul_f32_e32 v95, v95, v87
	v_mul_f32_e32 v88, v88, v80
	v_mul_f32_e32 v89, v89, v81
	v_mul_f32_e32 v90, v90, v82
	v_mul_f32_e32 v91, v91, v83
	v_cvt_pk_bf16_f32 v84, v92, v93
	v_cvt_pk_bf16_f32 v85, v94, v95
	v_cvt_pk_bf16_f32 v86, v88, v89
	v_cvt_pk_bf16_f32 v87, v90, v91
	global_store_dwordx4 v164, v[84:87], s[10:11]
	v_add_u32_e32 v165, 0x84000, v162
	v_mul_f32_e32 v76, v68, v76
	v_mul_f32_e32 v77, v69, v77
	v_mul_f32_e32 v78, v70, v78
	v_mul_f32_e32 v79, v71, v79
	v_mul_f32_e32 v72, v64, v72
	v_mul_f32_e32 v73, v65, v73
	v_mul_f32_e32 v74, v66, v74
	v_mul_f32_e32 v75, v67, v75
	v_mul_f32_e32 v68, v68, v229
	v_mul_f32_e32 v69, v69, v229
	v_mul_f32_e32 v70, v70, v229
	v_mul_f32_e32 v71, v71, v229
	v_mul_f32_e32 v64, v64, v229
	v_mul_f32_e32 v65, v65, v229
	v_mul_f32_e32 v66, v66, v229
	v_mul_f32_e32 v67, v67, v229
	v_exp_f32_e32 v68, v68
	v_exp_f32_e32 v69, v69
	v_exp_f32_e32 v70, v70
	v_exp_f32_e32 v71, v71
	v_exp_f32_e32 v64, v64
	v_exp_f32_e32 v65, v65
	v_exp_f32_e32 v66, v66
	v_exp_f32_e32 v67, v67
	v_add_f32_e32 v68, 1.0, v68
	v_add_f32_e32 v69, 1.0, v69
	v_add_f32_e32 v70, 1.0, v70
	v_add_f32_e32 v71, 1.0, v71
	v_add_f32_e32 v64, 1.0, v64
	v_add_f32_e32 v65, 1.0, v65
	v_add_f32_e32 v66, 1.0, v66
	v_add_f32_e32 v67, 1.0, v67
	v_rcp_f32_e32 v68, v68
	v_rcp_f32_e32 v69, v69
	v_rcp_f32_e32 v70, v70
	v_rcp_f32_e32 v71, v71
	v_rcp_f32_e32 v64, v64
	v_rcp_f32_e32 v65, v65
	v_rcp_f32_e32 v66, v66
	v_rcp_f32_e32 v67, v67
	v_mul_f32_e32 v76, v76, v237
	v_mul_f32_e32 v77, v77, v237
	v_mul_f32_e32 v78, v78, v237
	v_mul_f32_e32 v79, v79, v237
	v_mul_f32_e32 v72, v72, v237
	v_mul_f32_e32 v73, v73, v237
	v_mul_f32_e32 v74, v74, v237
	v_mul_f32_e32 v75, v75, v237
	v_mul_f32_e32 v76, v76, v68
	v_mul_f32_e32 v77, v77, v69
	v_mul_f32_e32 v78, v78, v70
	v_mul_f32_e32 v79, v79, v71
	v_mul_f32_e32 v72, v72, v64
	v_mul_f32_e32 v73, v73, v65
	v_mul_f32_e32 v74, v74, v66
	v_mul_f32_e32 v75, v75, v67
	v_cvt_pk_bf16_f32 v68, v76, v77
	v_cvt_pk_bf16_f32 v69, v78, v79
	v_cvt_pk_bf16_f32 v70, v72, v73
	v_cvt_pk_bf16_f32 v71, v74, v75
	global_store_dwordx4 v165, v[68:71], s[10:11]
	v_add_u32_e32 v164, 0x160000, v162
	v_mul_f32_e32 v60, v52, v60
	v_mul_f32_e32 v61, v53, v61
	v_mul_f32_e32 v62, v54, v62
	v_mul_f32_e32 v63, v55, v63
	v_mul_f32_e32 v56, v48, v56
	v_mul_f32_e32 v57, v49, v57
	v_mul_f32_e32 v58, v50, v58
	v_mul_f32_e32 v59, v51, v59
	v_mul_f32_e32 v52, v52, v230
	v_mul_f32_e32 v53, v53, v230
	v_mul_f32_e32 v54, v54, v230
	v_mul_f32_e32 v55, v55, v230
	v_mul_f32_e32 v48, v48, v230
	v_mul_f32_e32 v49, v49, v230
	v_mul_f32_e32 v50, v50, v230
	v_mul_f32_e32 v51, v51, v230
	v_exp_f32_e32 v52, v52
	v_exp_f32_e32 v53, v53
	v_exp_f32_e32 v54, v54
	v_exp_f32_e32 v55, v55
	v_exp_f32_e32 v48, v48
	v_exp_f32_e32 v49, v49
	v_exp_f32_e32 v50, v50
	v_exp_f32_e32 v51, v51
	v_add_f32_e32 v52, 1.0, v52
	v_add_f32_e32 v53, 1.0, v53
	v_add_f32_e32 v54, 1.0, v54
	v_add_f32_e32 v55, 1.0, v55
	v_add_f32_e32 v48, 1.0, v48
	v_add_f32_e32 v49, 1.0, v49
	v_add_f32_e32 v50, 1.0, v50
	v_add_f32_e32 v51, 1.0, v51
	v_rcp_f32_e32 v52, v52
	v_rcp_f32_e32 v53, v53
	v_rcp_f32_e32 v54, v54
	v_rcp_f32_e32 v55, v55
	v_rcp_f32_e32 v48, v48
	v_rcp_f32_e32 v49, v49
	v_rcp_f32_e32 v50, v50
	v_rcp_f32_e32 v51, v51
	v_mul_f32_e32 v60, v60, v238
	v_mul_f32_e32 v61, v61, v238
	v_mul_f32_e32 v62, v62, v238
	v_mul_f32_e32 v63, v63, v238
	v_mul_f32_e32 v56, v56, v238
	v_mul_f32_e32 v57, v57, v238
	v_mul_f32_e32 v58, v58, v238
	v_mul_f32_e32 v59, v59, v238
	v_mul_f32_e32 v60, v60, v52
	v_mul_f32_e32 v61, v61, v53
	v_mul_f32_e32 v62, v62, v54
	v_mul_f32_e32 v63, v63, v55
	v_mul_f32_e32 v56, v56, v48
	v_mul_f32_e32 v57, v57, v49
	v_mul_f32_e32 v58, v58, v50
	v_mul_f32_e32 v59, v59, v51
	v_cvt_pk_bf16_f32 v52, v60, v61
	v_cvt_pk_bf16_f32 v53, v62, v63
	v_cvt_pk_bf16_f32 v54, v56, v57
	v_cvt_pk_bf16_f32 v55, v58, v59
	global_store_dwordx4 v164, v[52:55], s[10:11]
	v_add_u32_e32 v165, 0x18c000, v162
	v_mul_f32_e32 v44, v36, v44
	v_mul_f32_e32 v45, v37, v45
	v_mul_f32_e32 v46, v38, v46
	v_mul_f32_e32 v47, v39, v47
	v_mul_f32_e32 v40, v32, v40
	v_mul_f32_e32 v41, v33, v41
	v_mul_f32_e32 v42, v34, v42
	v_mul_f32_e32 v43, v35, v43
	v_mul_f32_e32 v36, v36, v231
	v_mul_f32_e32 v37, v37, v231
	v_mul_f32_e32 v38, v38, v231
	v_mul_f32_e32 v39, v39, v231
	v_mul_f32_e32 v32, v32, v231
	v_mul_f32_e32 v33, v33, v231
	v_mul_f32_e32 v34, v34, v231
	v_mul_f32_e32 v35, v35, v231
; __device__ __forceinline__ unsigned cvt_pk_bf16(float lo, float hi) { unsigned r; asm volatile("v_cvt_pk_bf16_f32 %0, %1, %2" : "=v"(r) : "v"(lo), "v"(hi)); return r; }
; #define PG8_BAR __builtin_amdgcn_s_barrier()
; template <class Epi, class Sched, bool ALIGN_EPI = false, bool SP2 = false>
; __device__ __forceinline__ void gemm_phase(PG8_LAS unsigned char* lds, const Gemm g, const Sched& S, const Epi& E) {
;     ...
;         if constexpr (ALIGN_EPI) { if (wr == 0) PG8_BAR; }
;         if constexpr (!Epi::AFTER_DRAIN) { int ln_ = __builtin_amdgcn_mbcnt_hi(~0u, __builtin_amdgcn_mbcnt_lo(~0u, 0u)); asm volatile("" : "+v"(ln_)); E(acc, cur, wr, wc, ln_ & 15, ln_ >> 4); S.done(cur); }
;         if (!has_next) break;
; #pragma unroll
;         for (int a = 0; a < 2; ++a)
; #pragma unroll
;             for (int b = 0; b < 2; ++b)
; #pragma unroll
;                 for (int m = 0; m < 4; ++m)
; #pragma unroll
;                     for (int n = 0; n < 2; ++n) acc[a][b][m][n] = (f32x4){0.f, 0.f, 0.f, 0.f};
;         cur = nxt; cA = nA; cB = nB; ++ui;
;         if constexpr (ALIGN_EPI) { if (wr == 1) PG8_BAR; }
;     __device__ __forceinline__ void operator()(const f32x4 (&acc)[2][2][4][2], const Unit& u, int wr, int wc, int fr, int fq) const {
;     ...
;             for (int m = 0; m < 4; ++m) { const int row = row0 + ai * HALF + m * 16; const float rs = row_rstd(ssq, row, fr, fq), rs2 = rs * rs, nrl = -1.4426950408889634f * rs;
;                 float o[8];
; #pragma unroll
;                 for (int n = 0; n < 2; ++n) { const f32x4 g = acc[ai][0][m][n], gu = g * acc[ai][1][m][n] * rs2;
; #pragma unroll
;                     for (int j = 0; j < 4; ++j) o[4 * n + j] = gu[j] * __builtin_amdgcn_rcpf(1.0f + __builtin_amdgcn_exp2f(g[j] * nrl)); }
;                 u32x4 w; w.x = cvt_pk_bf16(o[0], o[1]); w.y = cvt_pk_bf16(o[2], o[3]); w.z = cvt_pk_bf16(o[4], o[5]); w.w = cvt_pk_bf16(o[6], o[7]);
;                 *(u32x4*)(ACT + (size_t)row * 5632 + ch0) = w;
;                 asm volatile("" ::: "memory"); }
	v_exp_f32_e32 v36, v36
	v_exp_f32_e32 v37, v37
	v_exp_f32_e32 v38, v38
	v_exp_f32_e32 v39, v39
	v_exp_f32_e32 v32, v32
	v_exp_f32_e32 v33, v33
	v_exp_f32_e32 v34, v34
	v_exp_f32_e32 v35, v35
	v_add_f32_e32 v36, 1.0, v36
	v_add_f32_e32 v37, 1.0, v37
	v_add_f32_e32 v38, 1.0, v38
	v_add_f32_e32 v39, 1.0, v39
	v_add_f32_e32 v32, 1.0, v32
	v_add_f32_e32 v33, 1.0, v33
	v_add_f32_e32 v34, 1.0, v34
	v_add_f32_e32 v35, 1.0, v35
	v_rcp_f32_e32 v36, v36
	v_rcp_f32_e32 v37, v37
	v_rcp_f32_e32 v38, v38
	v_rcp_f32_e32 v39, v39
	v_rcp_f32_e32 v32, v32
	v_rcp_f32_e32 v33, v33
	v_rcp_f32_e32 v34, v34
	v_rcp_f32_e32 v35, v35
	v_mul_f32_e32 v44, v44, v239
	v_mul_f32_e32 v45, v45, v239
	v_mul_f32_e32 v46, v46, v239
	v_mul_f32_e32 v47, v47, v239
	v_mul_f32_e32 v40, v40, v239
	v_mul_f32_e32 v41, v41, v239
	v_mul_f32_e32 v42, v42, v239
	v_mul_f32_e32 v43, v43, v239
	v_mul_f32_e32 v44, v44, v36
	v_mul_f32_e32 v45, v45, v37
	v_mul_f32_e32 v46, v46, v38
	v_mul_f32_e32 v47, v47, v39
	v_mul_f32_e32 v40, v40, v32
	v_mul_f32_e32 v41, v41, v33
	v_mul_f32_e32 v42, v42, v34
	v_mul_f32_e32 v43, v43, v35
	v_cvt_pk_bf16_f32 v36, v44, v45
	v_cvt_pk_bf16_f32 v37, v46, v47
	v_cvt_pk_bf16_f32 v38, v40, v41
	v_cvt_pk_bf16_f32 v39, v42, v43
	global_store_dwordx4 v165, v[36:39], s[10:11]
	v_add_u32_e32 v164, 0x1b8000, v162
	v_mul_f32_e32 v28, v20, v28
	v_mul_f32_e32 v29, v21, v29
	v_mul_f32_e32 v30, v22, v30
	v_mul_f32_e32 v31, v23, v31
	v_mul_f32_e32 v24, v16, v24
	v_mul_f32_e32 v25, v17, v25
	v_mul_f32_e32 v26, v18, v26
	v_mul_f32_e32 v27, v19, v27
	v_mul_f32_e32 v20, v20, v232
	v_mul_f32_e32 v21, v21, v232
	v_mul_f32_e32 v22, v22, v232
	v_mul_f32_e32 v23, v23, v232
	v_mul_f32_e32 v16, v16, v232
	v_mul_f32_e32 v17, v17, v232
	v_mul_f32_e32 v18, v18, v232
	v_mul_f32_e32 v19, v19, v232
	v_exp_f32_e32 v20, v20
	v_exp_f32_e32 v21, v21
	v_exp_f32_e32 v22, v22
	v_exp_f32_e32 v23, v23
	v_exp_f32_e32 v16, v16
	v_exp_f32_e32 v17, v17
	v_exp_f32_e32 v18, v18
	v_exp_f32_e32 v19, v19
	v_add_f32_e32 v20, 1.0, v20
	v_add_f32_e32 v21, 1.0, v21
	v_add_f32_e32 v22, 1.0, v22
	v_add_f32_e32 v23, 1.0, v23
	v_add_f32_e32 v16, 1.0, v16
	v_add_f32_e32 v17, 1.0, v17
	v_add_f32_e32 v18, 1.0, v18
	v_add_f32_e32 v19, 1.0, v19
	v_rcp_f32_e32 v20, v20
	v_rcp_f32_e32 v21, v21
	v_rcp_f32_e32 v22, v22
	v_rcp_f32_e32 v23, v23
	v_rcp_f32_e32 v16, v16
	v_rcp_f32_e32 v17, v17
	v_rcp_f32_e32 v18, v18
	v_rcp_f32_e32 v19, v19
	v_mul_f32_e32 v28, v28, v240
	v_mul_f32_e32 v29, v29, v240
	v_mul_f32_e32 v30, v30, v240
	v_mul_f32_e32 v31, v31, v240
	v_mul_f32_e32 v24, v24, v240
	v_mul_f32_e32 v25, v25, v240
	v_mul_f32_e32 v26, v26, v240
	v_mul_f32_e32 v27, v27, v240
	v_mul_f32_e32 v28, v28, v20
	v_mul_f32_e32 v29, v29, v21
	v_mul_f32_e32 v30, v30, v22
	v_mul_f32_e32 v31, v31, v23
	v_mul_f32_e32 v24, v24, v16
	v_mul_f32_e32 v25, v25, v17
	v_mul_f32_e32 v26, v26, v18
	v_mul_f32_e32 v27, v27, v19
	v_cvt_pk_bf16_f32 v20, v28, v29
	v_cvt_pk_bf16_f32 v21, v30, v31
	v_cvt_pk_bf16_f32 v22, v24, v25
	v_cvt_pk_bf16_f32 v23, v26, v27
	global_store_dwordx4 v164, v[20:23], s[10:11]
	v_add_u32_e32 v165, 0x1e4000, v162
	v_mul_f32_e32 v12, v8, v12
	v_mul_f32_e32 v13, v9, v13
	v_mul_f32_e32 v14, v10, v14
	v_mul_f32_e32 v15, v11, v15
	v_mul_f32_e32 v0, v4, v0
	v_mul_f32_e32 v1, v5, v1
	v_mul_f32_e32 v2, v6, v2
	v_mul_f32_e32 v3, v7, v3
	v_mul_f32_e32 v8, v8, v233
	v_mul_f32_e32 v9, v9, v233
	v_mul_f32_e32 v10, v10, v233
	v_mul_f32_e32 v11, v11, v233
	v_mul_f32_e32 v4, v4, v233
	v_mul_f32_e32 v5, v5, v233
	v_mul_f32_e32 v6, v6, v233
	v_mul_f32_e32 v7, v7, v233
	v_exp_f32_e32 v8, v8
	v_exp_f32_e32 v9, v9
	v_exp_f32_e32 v10, v10
	v_exp_f32_e32 v11, v11
	v_exp_f32_e32 v4, v4
	v_exp_f32_e32 v5, v5
	v_exp_f32_e32 v6, v6
	v_exp_f32_e32 v7, v7
	v_add_f32_e32 v8, 1.0, v8
	v_add_f32_e32 v9, 1.0, v9
	v_add_f32_e32 v10, 1.0, v10
	v_add_f32_e32 v11, 1.0, v11
	v_add_f32_e32 v4, 1.0, v4
	v_add_f32_e32 v5, 1.0, v5
	v_add_f32_e32 v6, 1.0, v6
	v_add_f32_e32 v7, 1.0, v7
	v_rcp_f32_e32 v8, v8
	v_rcp_f32_e32 v9, v9
	v_rcp_f32_e32 v10, v10
	v_rcp_f32_e32 v11, v11
	v_rcp_f32_e32 v4, v4
	v_rcp_f32_e32 v5, v5
	v_rcp_f32_e32 v6, v6
	v_rcp_f32_e32 v7, v7
	v_mul_f32_e32 v12, v12, v241
	v_mul_f32_e32 v13, v13, v241
	v_mul_f32_e32 v14, v14, v241
	v_mul_f32_e32 v15, v15, v241
	v_mul_f32_e32 v0, v0, v241
	v_mul_f32_e32 v1, v1, v241
	v_mul_f32_e32 v2, v2, v241
	v_mul_f32_e32 v3, v3, v241
	v_mul_f32_e32 v12, v12, v8
	v_mul_f32_e32 v13, v13, v9
	v_mul_f32_e32 v14, v14, v10
	v_mul_f32_e32 v15, v15, v11
	v_mul_f32_e32 v0, v0, v4
	v_mul_f32_e32 v1, v1, v5
	v_mul_f32_e32 v2, v2, v6
	v_mul_f32_e32 v3, v3, v7
	v_cvt_pk_bf16_f32 v8, v12, v13
	v_cvt_pk_bf16_f32 v9, v14, v15
	v_cvt_pk_bf16_f32 v10, v0, v1
	v_cvt_pk_bf16_f32 v11, v2, v3
	global_store_dwordx4 v165, v[8:11], s[10:11]
	s_andn2_b64 vcc, exec, s[8:9]
	s_mov_b64 s[8:9], -1
	s_cbranch_vccnz .LBB0_732
	s_and_b64 vcc, exec, s[64:65]
	s_cbranch_vccnz .LBB0_731
	s_barrier
	s_branch .LBB0_731

; __device__ __forceinline__ unsigned cvt_pk_bf16(float lo, float hi) { unsigned r; asm volatile("v_cvt_pk_bf16_f32 %0, %1, %2" : "=v"(r) : "v"(lo), "v"(hi)); return r; }
;     __device__ __forceinline__ void operator()(const f32x4 (&acc)[2][2][4][2], const Unit& u, int wr, int wc, int fr, int fq) const {
;     ...
;             for (int m = 0; m < 4; ++m) { const int row = row0 + ai * HALF + m * 16; const float rs = row_rstd(ssq, row, fr, fq), rs2 = rs * rs, nrl = -1.4426950408889634f * rs;
;                 float o[8];
; #pragma unroll
;                 for (int n = 0; n < 2; ++n) { const f32x4 g = acc[ai][0][m][n], gu = g * acc[ai][1][m][n] * rs2;
; #pragma unroll
;                     for (int j = 0; j < 4; ++j) o[4 * n + j] = gu[j] * __builtin_amdgcn_rcpf(1.0f + __builtin_amdgcn_exp2f(g[j] * nrl)); }
;                 u32x4 w; w.x = cvt_pk_bf16(o[0], o[1]); w.y = cvt_pk_bf16(o[2], o[3]); w.z = cvt_pk_bf16(o[4], o[5]); w.w = cvt_pk_bf16(o[6], o[7]);
;                 *(u32x4*)(ACT + (size_t)row * 5632 + ch0) = w;
.Lsw2_have:
	s_lshl_b32 s4, s78, 2
	s_lshl_b32 s5, s82, 1
	s_add_i32 s4, s4, s5
	v_add_u32_e32 v144, s4, v167
	v_lshrrev_b32_e32 v145, 4, v144
	v_and_b32_e32 v144, 15, v144
	v_lshlrev_b32_e32 v144, 6, v144
	v_lshl_add_u32 v144, v145, 12, v144
	s_and_b32 s4, s26, 7
	s_lshl_b32 s4, s4, 17
	v_add_u32_e32 v144, s4, v144
	s_mov_b32 s4, s55
	s_mov_b32 s5, s17
	s_nop 4
	global_load_dwordx4 v[242:245], v144, s[4:5] offset:256
	global_load_dwordx4 v[246:249], v144, s[4:5] offset:272
	global_load_dwordx4 v[242:245], v144, s[4:5] offset:288
	global_load_dwordx4 v[246:249], v144, s[4:5] offset:304
	v_and_b32_e32 v153, 15, v167
	v_lshrrev_b32_e32 v154, 4, v167
	s_lshl_b32 s4, s26, 8
	s_add_i32 s4, s4, s78
	v_or_b32_e32 v155, s4, v153
	s_lshl_b32 s4, s53, 7
	s_or_b32 s4, s4, s82
	v_lshl_add_u32 v162, v154, 3, s4
	v_lshlrev_b32_e32 v162, 1, v162
	v_mul_u32_u24_e32 v163, 0x2c00, v155
	v_add_u32_e32 v162, v162, v163
	v_mov_b32_e32 v164, v162
	v_mul_f32_e32 v124, v116, v124
	v_mul_f32_e32 v125, v117, v125
	v_mul_f32_e32 v126, v118, v126
	v_mul_f32_e32 v127, v119, v127
	v_mul_f32_e32 v120, v112, v120
	v_mul_f32_e32 v121, v113, v121
	v_mul_f32_e32 v122, v114, v122
	v_mul_f32_e32 v123, v115, v123
	v_mul_f32_e32 v116, v116, v226
	v_mul_f32_e32 v117, v117, v226
	v_mul_f32_e32 v118, v118, v226
	v_mul_f32_e32 v119, v119, v226
	v_mul_f32_e32 v112, v112, v226
	v_mul_f32_e32 v113, v113, v226
	v_mul_f32_e32 v114, v114, v226
	v_mul_f32_e32 v115, v115, v226
	v_exp_f32_e32 v116, v116
	v_exp_f32_e32 v117, v117
	v_exp_f32_e32 v118, v118
	v_exp_f32_e32 v119, v119
	v_exp_f32_e32 v112, v112
	v_exp_f32_e32 v113, v113
	v_exp_f32_e32 v114, v114
	v_exp_f32_e32 v115, v115
	v_add_f32_e32 v116, 1.0, v116
	v_add_f32_e32 v117, 1.0, v117
	v_add_f32_e32 v118, 1.0, v118
	v_add_f32_e32 v119, 1.0, v119
	v_add_f32_e32 v112, 1.0, v112
	v_add_f32_e32 v113, 1.0, v113
	v_add_f32_e32 v114, 1.0, v114
	v_add_f32_e32 v115, 1.0, v115
	v_rcp_f32_e32 v116, v116
	v_rcp_f32_e32 v117, v117
	v_rcp_f32_e32 v118, v118
	v_rcp_f32_e32 v119, v119
	v_rcp_f32_e32 v112, v112
	v_rcp_f32_e32 v113, v113
	v_rcp_f32_e32 v114, v114
	v_rcp_f32_e32 v115, v115
	v_mul_f32_e32 v124, v124, v234
	v_mul_f32_e32 v125, v125, v234
	v_mul_f32_e32 v126, v126, v234
	v_mul_f32_e32 v127, v127, v234
	v_mul_f32_e32 v120, v120, v234
	v_mul_f32_e32 v121, v121, v234
	v_mul_f32_e32 v122, v122, v234
	v_mul_f32_e32 v123, v123, v234
	v_mul_f32_e32 v124, v124, v116
	v_mul_f32_e32 v125, v125, v117
	v_mul_f32_e32 v126, v126, v118
	v_mul_f32_e32 v127, v127, v119
	v_mul_f32_e32 v120, v120, v112
	v_mul_f32_e32 v121, v121, v113
	v_mul_f32_e32 v122, v122, v114
	v_mul_f32_e32 v123, v123, v115
	v_cvt_pk_bf16_f32 v116, v124, v125
	v_cvt_pk_bf16_f32 v117, v126, v127
	v_cvt_pk_bf16_f32 v118, v120, v121
	v_cvt_pk_bf16_f32 v119, v122, v123
	global_store_dwordx4 v164, v[116:119], s[10:11]
	v_add_u32_e32 v165, 0x2c000, v162
	v_mul_f32_e32 v108, v100, v108
	v_mul_f32_e32 v109, v101, v109
	v_mul_f32_e32 v110, v102, v110
	v_mul_f32_e32 v111, v103, v111
	v_mul_f32_e32 v104, v96, v104
	v_mul_f32_e32 v105, v97, v105
	v_mul_f32_e32 v106, v98, v106
	v_mul_f32_e32 v107, v99, v107
	v_mul_f32_e32 v100, v100, v227
	v_mul_f32_e32 v101, v101, v227
	v_mul_f32_e32 v102, v102, v227
	v_mul_f32_e32 v103, v103, v227
	v_mul_f32_e32 v96, v96, v227
	v_mul_f32_e32 v97, v97, v227
	v_mul_f32_e32 v98, v98, v227
	v_mul_f32_e32 v99, v99, v227
	v_exp_f32_e32 v100, v100
	v_exp_f32_e32 v101, v101
	v_exp_f32_e32 v102, v102
	v_exp_f32_e32 v103, v103
	v_exp_f32_e32 v96, v96
	v_exp_f32_e32 v97, v97
	v_exp_f32_e32 v98, v98
	v_exp_f32_e32 v99, v99
	v_add_f32_e32 v100, 1.0, v100
	v_add_f32_e32 v101, 1.0, v101
	v_add_f32_e32 v102, 1.0, v102
	v_add_f32_e32 v103, 1.0, v103
	v_add_f32_e32 v96, 1.0, v96
	v_add_f32_e32 v97, 1.0, v97
	v_add_f32_e32 v98, 1.0, v98
	v_add_f32_e32 v99, 1.0, v99
	v_rcp_f32_e32 v100, v100
	v_rcp_f32_e32 v101, v101
	v_rcp_f32_e32 v102, v102
	v_rcp_f32_e32 v103, v103
	v_rcp_f32_e32 v96, v96
	v_rcp_f32_e32 v97, v97
	v_rcp_f32_e32 v98, v98
	v_rcp_f32_e32 v99, v99
	v_mul_f32_e32 v108, v108, v235
	v_mul_f32_e32 v109, v109, v235
	v_mul_f32_e32 v110, v110, v235
	v_mul_f32_e32 v111, v111, v235
	v_mul_f32_e32 v104, v104, v235
	v_mul_f32_e32 v105, v105, v235
	v_mul_f32_e32 v106, v106, v235
	v_mul_f32_e32 v107, v107, v235
	v_mul_f32_e32 v108, v108, v100
	v_mul_f32_e32 v109, v109, v101
	v_mul_f32_e32 v110, v110, v102
	v_mul_f32_e32 v111, v111, v103
	v_mul_f32_e32 v104, v104, v96
	v_mul_f32_e32 v105, v105, v97
	v_mul_f32_e32 v106, v106, v98
	v_mul_f32_e32 v107, v107, v99
	v_cvt_pk_bf16_f32 v100, v108, v109
	v_cvt_pk_bf16_f32 v101, v110, v111
	v_cvt_pk_bf16_f32 v102, v104, v105
	v_cvt_pk_bf16_f32 v103, v106, v107
	global_store_dwordx4 v165, v[100:103], s[10:11]
	v_add_u32_e32 v164, 0x58000, v162
	v_mul_f32_e32 v92, v84, v92
	v_mul_f32_e32 v93, v85, v93
	v_mul_f32_e32 v94, v86, v94
	v_mul_f32_e32 v95, v87, v95
	v_mul_f32_e32 v88, v80, v88
	v_mul_f32_e32 v89, v81, v89
	v_mul_f32_e32 v90, v82, v90
	v_mul_f32_e32 v91, v83, v91
	v_mul_f32_e32 v84, v84, v228
	v_mul_f32_e32 v85, v85, v228
	v_mul_f32_e32 v86, v86, v228
	v_mul_f32_e32 v87, v87, v228
	v_mul_f32_e32 v80, v80, v228
	v_mul_f32_e32 v81, v81, v228
	v_mul_f32_e32 v82, v82, v228
	v_mul_f32_e32 v83, v83, v228
	v_exp_f32_e32 v84, v84
	v_exp_f32_e32 v85, v85
	v_exp_f32_e32 v86, v86
	v_exp_f32_e32 v87, v87
	v_exp_f32_e32 v80, v80
	v_exp_f32_e32 v81, v81
	v_exp_f32_e32 v82, v82
	v_exp_f32_e32 v83, v83
	v_add_f32_e32 v84, 1.0, v84
	v_add_f32_e32 v85, 1.0, v85
	v_add_f32_e32 v86, 1.0, v86
	v_add_f32_e32 v87, 1.0, v87
	v_add_f32_e32 v80, 1.0, v80
	v_add_f32_e32 v81, 1.0, v81
	v_add_f32_e32 v82, 1.0, v82
	v_add_f32_e32 v83, 1.0, v83
	v_rcp_f32_e32 v84, v84
; __device__ __forceinline__ unsigned cvt_pk_bf16(float lo, float hi) { unsigned r; asm volatile("v_cvt_pk_bf16_f32 %0, %1, %2" : "=v"(r) : "v"(lo), "v"(hi)); return r; }
;     __device__ __forceinline__ void operator()(const f32x4 (&acc)[2][2][4][2], const Unit& u, int wr, int wc, int fr, int fq) const {
;     ...
;             for (int m = 0; m < 4; ++m) { const int row = row0 + ai * HALF + m * 16; const float rs = row_rstd(ssq, row, fr, fq), rs2 = rs * rs, nrl = -1.4426950408889634f * rs;
;                 float o[8];
; #pragma unroll
;                 for (int n = 0; n < 2; ++n) { const f32x4 g = acc[ai][0][m][n], gu = g * acc[ai][1][m][n] * rs2;
; #pragma unroll
;                     for (int j = 0; j < 4; ++j) o[4 * n + j] = gu[j] * __builtin_amdgcn_rcpf(1.0f + __builtin_amdgcn_exp2f(g[j] * nrl)); }
;                 u32x4 w; w.x = cvt_pk_bf16(o[0], o[1]); w.y = cvt_pk_bf16(o[2], o[3]); w.z = cvt_pk_bf16(o[4], o[5]); w.w = cvt_pk_bf16(o[6], o[7]);
;                 *(u32x4*)(ACT + (size_t)row * 5632 + ch0) = w;
	v_rcp_f32_e32 v85, v85
	v_rcp_f32_e32 v86, v86
	v_rcp_f32_e32 v87, v87
	v_rcp_f32_e32 v80, v80
	v_rcp_f32_e32 v81, v81
	v_rcp_f32_e32 v82, v82
	v_rcp_f32_e32 v83, v83
	v_mul_f32_e32 v92, v92, v236
	v_mul_f32_e32 v93, v93, v236
	v_mul_f32_e32 v94, v94, v236
	v_mul_f32_e32 v95, v95, v236
	v_mul_f32_e32 v88, v88, v236
	v_mul_f32_e32 v89, v89, v236
	v_mul_f32_e32 v90, v90, v236
	v_mul_f32_e32 v91, v91, v236
	v_mul_f32_e32 v92, v92, v84
	v_mul_f32_e32 v93, v93, v85
	v_mul_f32_e32 v94, v94, v86
	v_mul_f32_e32 v95, v95, v87
	v_mul_f32_e32 v88, v88, v80
	v_mul_f32_e32 v89, v89, v81
	v_mul_f32_e32 v90, v90, v82
	v_mul_f32_e32 v91, v91, v83
	v_cvt_pk_bf16_f32 v84, v92, v93
	v_cvt_pk_bf16_f32 v85, v94, v95
	v_cvt_pk_bf16_f32 v86, v88, v89
	v_cvt_pk_bf16_f32 v87, v90, v91
	global_store_dwordx4 v164, v[84:87], s[10:11]
	v_add_u32_e32 v165, 0x84000, v162
	v_mul_f32_e32 v76, v68, v76
	v_mul_f32_e32 v77, v69, v77
	v_mul_f32_e32 v78, v70, v78
	v_mul_f32_e32 v79, v71, v79
	v_mul_f32_e32 v72, v64, v72
	v_mul_f32_e32 v73, v65, v73
	v_mul_f32_e32 v74, v66, v74
	v_mul_f32_e32 v75, v67, v75
	v_mul_f32_e32 v68, v68, v229
	v_mul_f32_e32 v69, v69, v229
	v_mul_f32_e32 v70, v70, v229
	v_mul_f32_e32 v71, v71, v229
	v_mul_f32_e32 v64, v64, v229
	v_mul_f32_e32 v65, v65, v229
	v_mul_f32_e32 v66, v66, v229
	v_mul_f32_e32 v67, v67, v229
	v_exp_f32_e32 v68, v68
	v_exp_f32_e32 v69, v69
	v_exp_f32_e32 v70, v70
	v_exp_f32_e32 v71, v71
	v_exp_f32_e32 v64, v64
	v_exp_f32_e32 v65, v65
	v_exp_f32_e32 v66, v66
	v_exp_f32_e32 v67, v67
	v_add_f32_e32 v68, 1.0, v68
	v_add_f32_e32 v69, 1.0, v69
	v_add_f32_e32 v70, 1.0, v70
	v_add_f32_e32 v71, 1.0, v71
	v_add_f32_e32 v64, 1.0, v64
	v_add_f32_e32 v65, 1.0, v65
	v_add_f32_e32 v66, 1.0, v66
	v_add_f32_e32 v67, 1.0, v67
	v_rcp_f32_e32 v68, v68
	v_rcp_f32_e32 v69, v69
	v_rcp_f32_e32 v70, v70
	v_rcp_f32_e32 v71, v71
	v_rcp_f32_e32 v64, v64
	v_rcp_f32_e32 v65, v65
	v_rcp_f32_e32 v66, v66
	v_rcp_f32_e32 v67, v67
	v_mul_f32_e32 v76, v76, v237
	v_mul_f32_e32 v77, v77, v237
	v_mul_f32_e32 v78, v78, v237
	v_mul_f32_e32 v79, v79, v237
	v_mul_f32_e32 v72, v72, v237
	v_mul_f32_e32 v73, v73, v237
	v_mul_f32_e32 v74, v74, v237
	v_mul_f32_e32 v75, v75, v237
	v_mul_f32_e32 v76, v76, v68
	v_mul_f32_e32 v77, v77, v69
	v_mul_f32_e32 v78, v78, v70
	v_mul_f32_e32 v79, v79, v71
	v_mul_f32_e32 v72, v72, v64
	v_mul_f32_e32 v73, v73, v65
	v_mul_f32_e32 v74, v74, v66
	v_mul_f32_e32 v75, v75, v67
	v_cvt_pk_bf16_f32 v68, v76, v77
	v_cvt_pk_bf16_f32 v69, v78, v79
	v_cvt_pk_bf16_f32 v70, v72, v73
	v_cvt_pk_bf16_f32 v71, v74, v75
	global_store_dwordx4 v165, v[68:71], s[10:11]
	v_add_u32_e32 v164, 0x160000, v162
	v_mul_f32_e32 v60, v52, v60
	v_mul_f32_e32 v61, v53, v61
	v_mul_f32_e32 v62, v54, v62
	v_mul_f32_e32 v63, v55, v63
	v_mul_f32_e32 v56, v48, v56
	v_mul_f32_e32 v57, v49, v57
	v_mul_f32_e32 v58, v50, v58
	v_mul_f32_e32 v59, v51, v59
	v_mul_f32_e32 v52, v52, v230
	v_mul_f32_e32 v53, v53, v230
	v_mul_f32_e32 v54, v54, v230
	v_mul_f32_e32 v55, v55, v230
	v_mul_f32_e32 v48, v48, v230
	v_mul_f32_e32 v49, v49, v230
	v_mul_f32_e32 v50, v50, v230
	v_mul_f32_e32 v51, v51, v230
	v_exp_f32_e32 v52, v52
	v_exp_f32_e32 v53, v53
	v_exp_f32_e32 v54, v54
	v_exp_f32_e32 v55, v55
	v_exp_f32_e32 v48, v48
	v_exp_f32_e32 v49, v49
	v_exp_f32_e32 v50, v50
	v_exp_f32_e32 v51, v51
	v_add_f32_e32 v52, 1.0, v52
	v_add_f32_e32 v53, 1.0, v53
	v_add_f32_e32 v54, 1.0, v54
	v_add_f32_e32 v55, 1.0, v55
	v_add_f32_e32 v48, 1.0, v48
	v_add_f32_e32 v49, 1.0, v49
	v_add_f32_e32 v50, 1.0, v50
	v_add_f32_e32 v51, 1.0, v51
	v_rcp_f32_e32 v52, v52
	v_rcp_f32_e32 v53, v53
	v_rcp_f32_e32 v54, v54
	v_rcp_f32_e32 v55, v55
	v_rcp_f32_e32 v48, v48
	v_rcp_f32_e32 v49, v49
	v_rcp_f32_e32 v50, v50
	v_rcp_f32_e32 v51, v51
	v_mul_f32_e32 v60, v60, v238
	v_mul_f32_e32 v61, v61, v238
	v_mul_f32_e32 v62, v62, v238
	v_mul_f32_e32 v63, v63, v238
	v_mul_f32_e32 v56, v56, v238
	v_mul_f32_e32 v57, v57, v238
	v_mul_f32_e32 v58, v58, v238
	v_mul_f32_e32 v59, v59, v238
	v_mul_f32_e32 v60, v60, v52
	v_mul_f32_e32 v61, v61, v53
	v_mul_f32_e32 v62, v62, v54
	v_mul_f32_e32 v63, v63, v55
	v_mul_f32_e32 v56, v56, v48
	v_mul_f32_e32 v57, v57, v49
	v_mul_f32_e32 v58, v58, v50
	v_mul_f32_e32 v59, v59, v51
	v_cvt_pk_bf16_f32 v52, v60, v61
	v_cvt_pk_bf16_f32 v53, v62, v63
	v_cvt_pk_bf16_f32 v54, v56, v57
	v_cvt_pk_bf16_f32 v55, v58, v59
	global_store_dwordx4 v164, v[52:55], s[10:11]
	v_add_u32_e32 v165, 0x18c000, v162
	v_mul_f32_e32 v44, v36, v44
	v_mul_f32_e32 v45, v37, v45
	v_mul_f32_e32 v46, v38, v46
	v_mul_f32_e32 v47, v39, v47
	v_mul_f32_e32 v40, v32, v40
	v_mul_f32_e32 v41, v33, v41
	v_mul_f32_e32 v42, v34, v42
	v_mul_f32_e32 v43, v35, v43
	v_mul_f32_e32 v36, v36, v231
	v_mul_f32_e32 v37, v37, v231
	v_mul_f32_e32 v38, v38, v231
	v_mul_f32_e32 v39, v39, v231
	v_mul_f32_e32 v32, v32, v231
	v_mul_f32_e32 v33, v33, v231
	v_mul_f32_e32 v34, v34, v231
	v_mul_f32_e32 v35, v35, v231
; __device__ __forceinline__ unsigned cvt_pk_bf16(float lo, float hi) { unsigned r; asm volatile("v_cvt_pk_bf16_f32 %0, %1, %2" : "=v"(r) : "v"(lo), "v"(hi)); return r; }
; #define PG8_BAR __builtin_amdgcn_s_barrier()
; template <class Epi, class Sched, bool ALIGN_EPI = false, bool SP2 = false>
; __device__ __forceinline__ void gemm_phase(PG8_LAS unsigned char* lds, const Gemm g, const Sched& S, const Epi& E) {
;     ...
;         if constexpr (ALIGN_EPI) { if (wr == 0) PG8_BAR; }
;         if constexpr (!Epi::AFTER_DRAIN) { int ln_ = __builtin_amdgcn_mbcnt_hi(~0u, __builtin_amdgcn_mbcnt_lo(~0u, 0u)); asm volatile("" : "+v"(ln_)); E(acc, cur, wr, wc, ln_ & 15, ln_ >> 4); S.done(cur); }
;         if (!has_next) break;
; #pragma unroll
;         for (int a = 0; a < 2; ++a)
; #pragma unroll
;             for (int b = 0; b < 2; ++b)
; #pragma unroll
;                 for (int m = 0; m < 4; ++m)
; #pragma unroll
;                     for (int n = 0; n < 2; ++n) acc[a][b][m][n] = (f32x4){0.f, 0.f, 0.f, 0.f};
;         cur = nxt; cA = nA; cB = nB; ++ui;
;         if constexpr (ALIGN_EPI) { if (wr == 1) PG8_BAR; }
;     __device__ __forceinline__ void operator()(const f32x4 (&acc)[2][2][4][2], const Unit& u, int wr, int wc, int fr, int fq) const {
;     ...
;             for (int m = 0; m < 4; ++m) { const int row = row0 + ai * HALF + m * 16; const float rs = row_rstd(ssq, row, fr, fq), rs2 = rs * rs, nrl = -1.4426950408889634f * rs;
;                 float o[8];
; #pragma unroll
;                 for (int n = 0; n < 2; ++n) { const f32x4 g = acc[ai][0][m][n], gu = g * acc[ai][1][m][n] * rs2;
; #pragma unroll
;                     for (int j = 0; j < 4; ++j) o[4 * n + j] = gu[j] * __builtin_amdgcn_rcpf(1.0f + __builtin_amdgcn_exp2f(g[j] * nrl)); }
;                 u32x4 w; w.x = cvt_pk_bf16(o[0], o[1]); w.y = cvt_pk_bf16(o[2], o[3]); w.z = cvt_pk_bf16(o[4], o[5]); w.w = cvt_pk_bf16(o[6], o[7]);
;                 *(u32x4*)(ACT + (size_t)row * 5632 + ch0) = w;
;                 asm volatile("" ::: "memory"); }
	v_exp_f32_e32 v36, v36
	v_exp_f32_e32 v37, v37
	v_exp_f32_e32 v38, v38
	v_exp_f32_e32 v39, v39
	v_exp_f32_e32 v32, v32
	v_exp_f32_e32 v33, v33
	v_exp_f32_e32 v34, v34
	v_exp_f32_e32 v35, v35
	v_add_f32_e32 v36, 1.0, v36
	v_add_f32_e32 v37, 1.0, v37
	v_add_f32_e32 v38, 1.0, v38
	v_add_f32_e32 v39, 1.0, v39
	v_add_f32_e32 v32, 1.0, v32
	v_add_f32_e32 v33, 1.0, v33
	v_add_f32_e32 v34, 1.0, v34
	v_add_f32_e32 v35, 1.0, v35
	v_rcp_f32_e32 v36, v36
	v_rcp_f32_e32 v37, v37
	v_rcp_f32_e32 v38, v38
	v_rcp_f32_e32 v39, v39
	v_rcp_f32_e32 v32, v32
	v_rcp_f32_e32 v33, v33
	v_rcp_f32_e32 v34, v34
	v_rcp_f32_e32 v35, v35
	v_mul_f32_e32 v44, v44, v239
	v_mul_f32_e32 v45, v45, v239
	v_mul_f32_e32 v46, v46, v239
	v_mul_f32_e32 v47, v47, v239
	v_mul_f32_e32 v40, v40, v239
	v_mul_f32_e32 v41, v41, v239
	v_mul_f32_e32 v42, v42, v239
	v_mul_f32_e32 v43, v43, v239
	v_mul_f32_e32 v44, v44, v36
	v_mul_f32_e32 v45, v45, v37
	v_mul_f32_e32 v46, v46, v38
	v_mul_f32_e32 v47, v47, v39
	v_mul_f32_e32 v40, v40, v32
	v_mul_f32_e32 v41, v41, v33
	v_mul_f32_e32 v42, v42, v34
	v_mul_f32_e32 v43, v43, v35
	v_cvt_pk_bf16_f32 v36, v44, v45
	v_cvt_pk_bf16_f32 v37, v46, v47
	v_cvt_pk_bf16_f32 v38, v40, v41
	v_cvt_pk_bf16_f32 v39, v42, v43
	global_store_dwordx4 v165, v[36:39], s[10:11]
	v_add_u32_e32 v164, 0x1b8000, v162
	v_mul_f32_e32 v28, v20, v28
	v_mul_f32_e32 v29, v21, v29
	v_mul_f32_e32 v30, v22, v30
	v_mul_f32_e32 v31, v23, v31
	v_mul_f32_e32 v24, v16, v24
	v_mul_f32_e32 v25, v17, v25
	v_mul_f32_e32 v26, v18, v26
	v_mul_f32_e32 v27, v19, v27
	v_mul_f32_e32 v20, v20, v232
	v_mul_f32_e32 v21, v21, v232
	v_mul_f32_e32 v22, v22, v232
	v_mul_f32_e32 v23, v23, v232
	v_mul_f32_e32 v16, v16, v232
	v_mul_f32_e32 v17, v17, v232
	v_mul_f32_e32 v18, v18, v232
	v_mul_f32_e32 v19, v19, v232
	v_exp_f32_e32 v20, v20
	v_exp_f32_e32 v21, v21
	v_exp_f32_e32 v22, v22
	v_exp_f32_e32 v23, v23
	v_exp_f32_e32 v16, v16
	v_exp_f32_e32 v17, v17
	v_exp_f32_e32 v18, v18
	v_exp_f32_e32 v19, v19
	v_add_f32_e32 v20, 1.0, v20
	v_add_f32_e32 v21, 1.0, v21
	v_add_f32_e32 v22, 1.0, v22
	v_add_f32_e32 v23, 1.0, v23
	v_add_f32_e32 v16, 1.0, v16
	v_add_f32_e32 v17, 1.0, v17
	v_add_f32_e32 v18, 1.0, v18
	v_add_f32_e32 v19, 1.0, v19
	v_rcp_f32_e32 v20, v20
	v_rcp_f32_e32 v21, v21
	v_rcp_f32_e32 v22, v22
	v_rcp_f32_e32 v23, v23
	v_rcp_f32_e32 v16, v16
	v_rcp_f32_e32 v17, v17
	v_rcp_f32_e32 v18, v18
	v_rcp_f32_e32 v19, v19
	v_mul_f32_e32 v28, v28, v240
	v_mul_f32_e32 v29, v29, v240
	v_mul_f32_e32 v30, v30, v240
	v_mul_f32_e32 v31, v31, v240
	v_mul_f32_e32 v24, v24, v240
	v_mul_f32_e32 v25, v25, v240
	v_mul_f32_e32 v26, v26, v240
	v_mul_f32_e32 v27, v27, v240
	v_mul_f32_e32 v28, v28, v20
	v_mul_f32_e32 v29, v29, v21
	v_mul_f32_e32 v30, v30, v22
	v_mul_f32_e32 v31, v31, v23
	v_mul_f32_e32 v24, v24, v16
	v_mul_f32_e32 v25, v25, v17
	v_mul_f32_e32 v26, v26, v18
	v_mul_f32_e32 v27, v27, v19
	v_cvt_pk_bf16_f32 v20, v28, v29
	v_cvt_pk_bf16_f32 v21, v30, v31
	v_cvt_pk_bf16_f32 v22, v24, v25
	v_cvt_pk_bf16_f32 v23, v26, v27
	global_store_dwordx4 v164, v[20:23], s[10:11]
	v_add_u32_e32 v165, 0x1e4000, v162
	v_mul_f32_e32 v12, v8, v12
	v_mul_f32_e32 v13, v9, v13
	v_mul_f32_e32 v14, v10, v14
	v_mul_f32_e32 v15, v11, v15
	v_mul_f32_e32 v0, v4, v0
	v_mul_f32_e32 v1, v5, v1
	v_mul_f32_e32 v2, v6, v2
	v_mul_f32_e32 v3, v7, v3
	v_mul_f32_e32 v8, v8, v233
	v_mul_f32_e32 v9, v9, v233
	v_mul_f32_e32 v10, v10, v233
	v_mul_f32_e32 v11, v11, v233
	v_mul_f32_e32 v4, v4, v233
	v_mul_f32_e32 v5, v5, v233
	v_mul_f32_e32 v6, v6, v233
	v_mul_f32_e32 v7, v7, v233
	v_exp_f32_e32 v8, v8
	v_exp_f32_e32 v9, v9
	v_exp_f32_e32 v10, v10
	v_exp_f32_e32 v11, v11
	v_exp_f32_e32 v4, v4
	v_exp_f32_e32 v5, v5
	v_exp_f32_e32 v6, v6
	v_exp_f32_e32 v7, v7
	v_add_f32_e32 v8, 1.0, v8
	v_add_f32_e32 v9, 1.0, v9
	v_add_f32_e32 v10, 1.0, v10
	v_add_f32_e32 v11, 1.0, v11
	v_add_f32_e32 v4, 1.0, v4
	v_add_f32_e32 v5, 1.0, v5
	v_add_f32_e32 v6, 1.0, v6
	v_add_f32_e32 v7, 1.0, v7
	v_rcp_f32_e32 v8, v8
	v_rcp_f32_e32 v9, v9
	v_rcp_f32_e32 v10, v10
	v_rcp_f32_e32 v11, v11
	v_rcp_f32_e32 v4, v4
	v_rcp_f32_e32 v5, v5
	v_rcp_f32_e32 v6, v6
	v_rcp_f32_e32 v7, v7
	v_mul_f32_e32 v12, v12, v241
	v_mul_f32_e32 v13, v13, v241
	v_mul_f32_e32 v14, v14, v241
	v_mul_f32_e32 v15, v15, v241
	v_mul_f32_e32 v0, v0, v241
	v_mul_f32_e32 v1, v1, v241
	v_mul_f32_e32 v2, v2, v241
	v_mul_f32_e32 v3, v3, v241
	v_mul_f32_e32 v12, v12, v8
	v_mul_f32_e32 v13, v13, v9
	v_mul_f32_e32 v14, v14, v10
	v_mul_f32_e32 v15, v15, v11
	v_mul_f32_e32 v0, v0, v4
	v_mul_f32_e32 v1, v1, v5
	v_mul_f32_e32 v2, v2, v6
	v_mul_f32_e32 v3, v3, v7
	v_cvt_pk_bf16_f32 v8, v12, v13
	v_cvt_pk_bf16_f32 v9, v14, v15
	v_cvt_pk_bf16_f32 v10, v0, v1
	v_cvt_pk_bf16_f32 v11, v2, v3
	global_store_dwordx4 v165, v[8:11], s[10:11]
	s_andn2_b64 vcc, exec, s[8:9]
	s_mov_b64 s[8:9], -1
	s_cbranch_vccnz .LBB0_1283
	s_and_b64 vcc, exec, s[66:67]
	s_cbranch_vccnz .LBB0_1282
	s_barrier
	s_branch .LBB0_1282
